# chained MFMA order, no per-segment s_setprio; one static s_setprio 1 for waves 4-7 during the GEMM phases
# baseline (speedup 1.0000x reference)
; #define PG8_STAGE(bufoff, gbase, voff) do { const char* gb_ = (const char*)(gbase); asm volatile("" : "+s"(gb_)); _Pragma("unroll") for (int _i = 0; _i < 2; ++_i) { unsigned vo_ = (voff)[_i]; asm volatile("" : "+v"(vo_));        \
;         __builtin_amdgcn_global_load_lds((const unsigned*)(gb_ + vo_), (PG8_LAS unsigned*)(lds + (bufoff) + ldsw + _i * 8192), 16, 0, 0); } } while (0)
; #define PG8_BAR __builtin_amdgcn_s_barrier()
; template <class Epi, class Sched, bool ALIGN_EPI = false, bool SP2 = false>
; __device__ __forceinline__ void gemm_phase(PG8_LAS unsigned char* lds, const Gemm g, const Sched& S, const Epi& E) {
;     int tid_ = threadIdx.x; asm volatile("" : "+v"(tid_));
;     const int tid = tid_, wid = __builtin_amdgcn_readfirstlane(tid >> 6), lane = tid & 63, wr = wid >> 2, wc = wid & 3, fr = lane & 15, fq = lane >> 4;
;     const int K = g.K, nt = K / BK;
;     unsigned voffA[2], voffB[2];
; #pragma unroll
;     for (int i = 0; i < 2; ++i) { int R, C; stage_rc(tid * 16 + i * 8192, R, C); const int Rb = Epi::PERM ? ((R & ~31) + perm32(R & 31)) : R;
;         voffA[i] = (unsigned)(R * K + C) * 2u; voffB[i] = (unsigned)(Rb * K + C) * 2u; }
;     ...
;     const char* cA = (const char*)g.A + (size_t)cur.pm * tstep; const char* cB = (const char*)g.Bt + (size_t)cur.pn * tstep;
;     S.a_ready(cur);
;     if constexpr (SP2) {
;         PG8_STAGE(PG8_SB(0, 0), cB, voffB); PG8_STAGE(PG8_SB(0, 1), cB + hstep, voffB); PG8_STAGE(PG8_SA(0, 0), cA, voffA); PG8_STAGE(PG8_SA(0, 1), cA + hstep, voffA);
;         if (wr == 1) PG8_BAR;
.LBB0_222:
	s_andn2_b64 vcc, exec, s[0:1]
	v_readlane_b32 s40, v241, 42
	v_writelane_b32 v241, s36, 48
	s_cbranch_vccnz .LBB0_325
	v_readlane_b32 s0, v243, 22
	s_waitcnt vmcnt(0)
	v_mov_b32_e32 v2, v0
	v_readlane_b32 s1, v243, 23
	s_andn2_b64 vcc, exec, s[0:1]
	v_readfirstlane_b32 s0, v2
	s_cbranch_vccnz .LBB0_279
	v_bfe_i32 v4, v2, 27, 1
	s_waitcnt lgkmcnt(0)
	v_lshlrev_b32_e32 v3, 4, v2
	v_lshrrev_b32_e32 v4, 22, v4
	v_add_u32_e32 v4, v3, v4
	v_and_b32_e32 v4, 0xfffffc00, v4
	v_sub_u32_e32 v4, v3, v4
	v_ashrrev_i32_e32 v1, 31, v2
	v_lshrrev_b32_e32 v5, 4, v4
	v_lshrrev_b32_e32 v1, 26, v1
	v_bitop3_b32 v4, v5, v4, 32 bitop3:0x6c
	v_add_u32_e32 v1, v2, v1
	v_ashrrev_i32_e32 v6, 31, v4
	v_ashrrev_i32_e32 v1, 6, v1
	v_lshrrev_b32_e32 v6, 26, v6
	v_lshlrev_b32_e32 v5, 3, v1
	v_add_u32_e32 v6, v4, v6
	v_and_b32_e32 v5, -16, v5
	v_ashrrev_i32_e32 v7, 6, v6
	v_and_b32_e32 v6, 0xc0, v6
	v_add_u32_e32 v5, v7, v5
	v_sub_u32_e32 v4, v4, v6
	v_lshlrev_b32_e32 v1, 5, v1
	v_ashrrev_i16_sdwa v4, v217, sext(v4) dst_sel:DWORD dst_unused:UNUSED_PAD src0_sel:DWORD src1_sel:BYTE_0
	v_lshlrev_b32_e32 v6, 1, v5
	v_lshrrev_b32_e32 v8, 2, v5
	v_and_b32_e32 v7, 3, v7
	s_mov_b32 s2, 0xfffe0
	v_and_b32_e32 v1, 32, v1
	v_bfe_i32 v4, v4, 0, 16
	v_and_b32_e32 v6, 24, v6
	v_and_b32_e32 v8, 4, v8
	v_and_or_b32 v7, v5, s2, v7
	v_or3_b32 v6, v7, v8, v6
	v_add_lshl_u32 v4, v1, v4, 1
	v_add_u32_e32 v3, 0x2000, v3
	v_lshl_add_u32 v1, v5, 12, v4
	v_lshl_add_u32 v189, v6, 12, v4
	v_ashrrev_i32_e32 v4, 31, v3
	v_lshrrev_b32_e32 v4, 22, v4
	v_add_u32_e32 v4, v3, v4
	v_ashrrev_i32_e32 v4, 10, v4
	v_mul_i32_i24_e32 v5, 0x400, v4
	v_sub_u32_e32 v3, v3, v5
	v_lshrrev_b32_e32 v5, 4, v3
	v_bitop3_b32 v3, v5, v3, 32 bitop3:0x6c
	v_ashrrev_i32_e32 v6, 31, v3
	v_lshrrev_b32_e32 v6, 26, v6
	v_lshlrev_b32_e32 v5, 3, v4
	v_add_u32_e32 v6, v3, v6
	v_and_b32_e32 v5, -16, v5
	v_ashrrev_i32_e32 v7, 6, v6
	v_and_b32_e32 v6, 0xc0, v6
	v_add_u32_e32 v5, v7, v5
	v_sub_u32_e32 v3, v3, v6
	v_and_b32_e32 v7, 3, v7
	s_ashr_i32 s6, s0, 6
	s_ashr_i32 s1, s0, 8
	v_lshlrev_b32_e32 v4, 5, v4
	v_ashrrev_i16_sdwa v3, v217, sext(v3) dst_sel:DWORD dst_unused:UNUSED_PAD src0_sel:DWORD src1_sel:BYTE_0
	v_lshlrev_b32_e32 v6, 1, v5
	v_lshrrev_b32_e32 v8, 2, v5
	v_and_or_b32 v7, v5, s2, v7
	s_lshl_b32 s12, s6, 10
	v_readlane_b32 s2, v242, 18
	v_readlane_b32 s4, v241, 44
	v_and_b32_e32 v4, 32, v4
	v_bfe_i32 v3, v3, 0, 16
	v_and_b32_e32 v6, 24, v6
	v_and_b32_e32 v8, 4, v8
	v_readlane_b32 s3, v242, 19
	s_add_u32 s2, s4, s2
	v_readlane_b32 s4, v241, 45
	v_or3_b32 v6, v7, v8, v6
	v_add_lshl_u32 v3, v4, v3, 1
	s_addc_u32 s3, s4, s3
	v_lshl_add_u32 v191, v5, 12, v3
	v_lshl_add_u32 v219, v6, 12, v3
	s_mov_b64 s[4:5], s[2:3]
	s_add_i32 s13, s12, 0
	v_mov_b32_e32 v3, v189
	s_add_i32 m0, s13, 0x10000
	s_nop 0
	global_load_lds_dwordx4 v3, s[4:5]
	v_mov_b32_e32 v3, v219
	s_add_i32 m0, s13, 0x12000
	s_nop 0
	global_load_lds_dwordx4 v3, s[4:5]
	s_add_u32 s4, s2, 0x80000
	s_addc_u32 s5, s3, 0
	v_mov_b32_e32 v3, v189
	s_add_i32 m0, s13, 0x14000
	s_add_i32 s14, s13, 0x2000
	global_load_lds_dwordx4 v3, s[4:5]
	v_mov_b32_e32 v3, v219
	s_add_i32 m0, s13, 0x16000
	s_add_i32 s15, s13, 0x4000
	global_load_lds_dwordx4 v3, s[4:5]
	v_readlane_b32 s4, v242, 24
	v_readlane_b32 s5, v242, 25
	v_mov_b32_e32 v3, v1
	s_mov_b32 m0, s13
	s_add_i32 s16, s13, 0x6000
	s_nop 1
	global_load_lds_dwordx4 v3, s[4:5]
	v_mov_b32_e32 v3, v191
	s_mov_b32 m0, s14
	s_cmp_eq_u32 s1, 1
	global_load_lds_dwordx4 v3, s[4:5]
	v_readlane_b32 s4, v242, 22
	v_readlane_b32 s5, v242, 23
	v_mov_b32_e32 v3, v1
	s_mov_b32 m0, s15
	s_nop 2
	global_load_lds_dwordx4 v3, s[4:5]
	v_mov_b32_e32 v3, v191
	s_mov_b32 m0, s16
	s_nop 0
	global_load_lds_dwordx4 v3, s[4:5]
	s_cselect_b64 s[4:5], -1, 0
	s_cmp_lg_u32 s1, 1
	s_cbranch_scc1 .LBB0_226
	s_setprio 1
	s_barrier

; #define PG8_WAIT_V(n) asm volatile("s_waitcnt vmcnt(" #n ")" ::: "memory")
; #define PG8_BAR __builtin_amdgcn_s_barrier()
; template <class Epi, class Sched, bool ALIGN_EPI = false, bool SP2 = false>
; __device__ __forceinline__ void gemm_phase(PG8_LAS unsigned char* lds, const Gemm g, const Sched& S, const Epi& E) {
;     ...
;     PG8_WAIT_V(0);
;     if constexpr (!ALIGN_EPI) { if (wr == 0) PG8_BAR; }
;     PG8_BAR;
.LBB0_278:
	s_setprio 0
	s_waitcnt vmcnt(0)
	v_readlane_b32 s4, v243, 2
	v_readlane_b32 s5, v243, 3
	s_movk_i32 s48, 0x2000
	s_movk_i32 s49, 0x3000
	s_movk_i32 s46, 0x1ff
	v_readlane_b32 s50, v241, 17
	s_mov_b32 s51, 0xd800000
	v_readlane_b32 s36, v241, 48
	s_barrier
	v_readlane_b32 s6, v243, 4
	v_readlane_b32 s7, v243, 5
	v_readlane_b32 s8, v243, 6
	v_readlane_b32 s9, v243, 7
	v_readlane_b32 s10, v243, 8
	v_readlane_b32 s11, v243, 9
	v_readlane_b32 s12, v243, 10
	v_readlane_b32 s13, v243, 11
	v_readlane_b32 s14, v243, 12
	v_readlane_b32 s15, v243, 13
	v_readlane_b32 s16, v243, 14
	v_readlane_b32 s17, v243, 15
	v_readlane_b32 s18, v243, 16
	v_readlane_b32 s19, v243, 17

; #define PG8_STAGE(bufoff, gbase, voff) do { const char* gb_ = (const char*)(gbase); asm volatile("" : "+s"(gb_)); _Pragma("unroll") for (int _i = 0; _i < 2; ++_i) { unsigned vo_ = (voff)[_i]; asm volatile("" : "+v"(vo_));        \
;         __builtin_amdgcn_global_load_lds((const unsigned*)(gb_ + vo_), (PG8_LAS unsigned*)(lds + (bufoff) + ldsw + _i * 8192), 16, 0, 0); } } while (0)
; #define PG8_BAR __builtin_amdgcn_s_barrier()
; template <class Epi, class Sched, bool ALIGN_EPI = false, bool SP2 = false>
; __device__ __forceinline__ void gemm_phase(PG8_LAS unsigned char* lds, const Gemm g, const Sched& S, const Epi& E) {
;     int tid_ = threadIdx.x; asm volatile("" : "+v"(tid_));
;     const int tid = tid_, wid = __builtin_amdgcn_readfirstlane(tid >> 6), lane = tid & 63, wr = wid >> 2, wc = wid & 3, fr = lane & 15, fq = lane >> 4;
;     const int K = g.K, nt = K / BK;
;     unsigned voffA[2], voffB[2];
; #pragma unroll
;     for (int i = 0; i < 2; ++i) { int R, C; stage_rc(tid * 16 + i * 8192, R, C); const int Rb = Epi::PERM ? ((R & ~31) + perm32(R & 31)) : R;
;         voffA[i] = (unsigned)(R * K + C) * 2u; voffB[i] = (unsigned)(Rb * K + C) * 2u; }
;     ...
;     const char* cA = (const char*)g.A + (size_t)cur.pm * tstep; const char* cB = (const char*)g.Bt + (size_t)cur.pn * tstep;
;     S.a_ready(cur);
;     if constexpr (SP2) {
;         PG8_STAGE(PG8_SB(0, 0), cB, voffB); PG8_STAGE(PG8_SB(0, 1), cB + hstep, voffB); PG8_STAGE(PG8_SA(0, 0), cA, voffA); PG8_STAGE(PG8_SA(0, 1), cA + hstep, voffA);
;         if (wr == 1) PG8_BAR;
.LBB0_542:
	s_andn2_b64 vcc, exec, s[0:1]
	v_readlane_b32 s0, v243, 63
	v_readlane_b32 s1, v242, 0
	s_nop 1
	v_cndmask_b32_e64 v1, 0, 1, s[0:1]
	v_cmp_ne_u32_e64 s[36:37], 1, v1
	s_cbranch_vccnz .LBB0_622
	s_waitcnt vmcnt(0)
	v_mov_b32_e32 v2, v0
	s_and_b64 vcc, exec, s[36:37]
	v_readfirstlane_b32 s14, v2
	s_cbranch_vccnz .LBB0_575
	v_bfe_i32 v4, v2, 27, 1
	s_waitcnt lgkmcnt(0)
	v_lshlrev_b32_e32 v3, 4, v2
	v_lshrrev_b32_e32 v4, 22, v4
	v_add_u32_e32 v4, v3, v4
	v_and_b32_e32 v4, 0xfffffc00, v4
	v_sub_u32_e32 v4, v3, v4
	v_ashrrev_i32_e32 v1, 31, v2
	v_lshrrev_b32_e32 v5, 4, v4
	v_lshrrev_b32_e32 v1, 26, v1
	v_bitop3_b32 v4, v5, v4, 32 bitop3:0x6c
	v_add_u32_e32 v1, v2, v1
	v_ashrrev_i32_e32 v6, 31, v4
	v_ashrrev_i32_e32 v1, 6, v1
	v_lshrrev_b32_e32 v6, 26, v6
	v_lshlrev_b32_e32 v5, 3, v1
	v_add_u32_e32 v6, v4, v6
	v_and_b32_e32 v5, -16, v5
	v_ashrrev_i32_e32 v7, 6, v6
	v_and_b32_e32 v6, 0xc0, v6
	v_add_u32_e32 v5, v7, v5
	v_sub_u32_e32 v4, v4, v6
	v_lshlrev_b32_e32 v1, 5, v1
	v_ashrrev_i16_sdwa v4, v217, sext(v4) dst_sel:DWORD dst_unused:UNUSED_PAD src0_sel:DWORD src1_sel:BYTE_0
	v_lshlrev_b32_e32 v6, 1, v5
	v_lshrrev_b32_e32 v8, 2, v5
	v_and_b32_e32 v7, 3, v7
	s_mov_b32 s1, 0xfffe0
	v_and_b32_e32 v1, 32, v1
	v_bfe_i32 v4, v4, 0, 16
	v_and_b32_e32 v6, 24, v6
	v_and_b32_e32 v8, 4, v8
	v_and_or_b32 v7, v5, s1, v7
	v_or3_b32 v6, v7, v8, v6
	v_add_lshl_u32 v4, v1, v4, 1
	v_add_u32_e32 v3, 0x2000, v3
	v_lshl_add_u32 v1, v5, 12, v4
	v_lshl_add_u32 v162, v6, 12, v4
	v_ashrrev_i32_e32 v4, 31, v3
	v_lshrrev_b32_e32 v4, 22, v4
	v_add_u32_e32 v4, v3, v4
	v_ashrrev_i32_e32 v4, 10, v4
	v_mul_i32_i24_e32 v5, 0x400, v4
	v_sub_u32_e32 v3, v3, v5
	v_lshrrev_b32_e32 v5, 4, v3
	v_bitop3_b32 v3, v5, v3, 32 bitop3:0x6c
	v_ashrrev_i32_e32 v6, 31, v3
	v_lshrrev_b32_e32 v6, 26, v6
	v_lshlrev_b32_e32 v5, 3, v4
	v_add_u32_e32 v6, v3, v6
	v_readlane_b32 s0, v241, 44
	v_and_b32_e32 v5, -16, v5
	v_ashrrev_i32_e32 v7, 6, v6
	s_add_u32 s15, s0, 0x1c00000
	v_readlane_b32 s0, v241, 45
	v_add_u32_e32 v5, v7, v5
	v_and_b32_e32 v6, 0xc0, v6
	v_and_b32_e32 v7, 3, v7
	s_addc_u32 s16, s0, 0
	v_sub_u32_e32 v3, v3, v6
	v_and_or_b32 v7, v5, s1, v7
	s_ashr_i32 s1, s14, 6
	s_ashr_i32 s0, s14, 8
	v_lshlrev_b32_e32 v4, 5, v4
	v_ashrrev_i16_sdwa v3, v217, sext(v3) dst_sel:DWORD dst_unused:UNUSED_PAD src0_sel:DWORD src1_sel:BYTE_0
	v_lshlrev_b32_e32 v6, 1, v5
	v_lshrrev_b32_e32 v8, 2, v5
	s_lshl_b32 s17, s1, 10
	v_readlane_b32 s2, v242, 28
	v_and_b32_e32 v4, 32, v4
	v_bfe_i32 v3, v3, 0, 16
	v_and_b32_e32 v6, 24, v6
	v_and_b32_e32 v8, 4, v8
	v_readlane_b32 s3, v242, 29
	s_add_u32 s6, s15, s2
	v_or3_b32 v6, v7, v8, v6
	v_add_lshl_u32 v3, v4, v3, 1
	s_addc_u32 s7, s16, s3
	v_lshl_add_u32 v164, v5, 12, v3
	v_lshl_add_u32 v206, v6, 12, v3
	s_mov_b64 s[2:3], s[6:7]
	s_add_i32 s18, s17, 0
	v_mov_b32_e32 v3, v162
	s_add_i32 m0, s18, 0x10000
	s_nop 0
	global_load_lds_dwordx4 v3, s[2:3]
	v_mov_b32_e32 v3, v206
	s_add_i32 m0, s18, 0x12000
	s_nop 0
	global_load_lds_dwordx4 v3, s[2:3]
	s_add_u32 s2, s6, 0x80000
	s_addc_u32 s3, s7, 0
	v_mov_b32_e32 v3, v162
	s_add_i32 m0, s18, 0x14000
	s_add_i32 s19, s18, 0x2000
	global_load_lds_dwordx4 v3, s[2:3]
	v_mov_b32_e32 v3, v206
	s_add_i32 m0, s18, 0x16000
	s_add_i32 s20, s18, 0x4000
	global_load_lds_dwordx4 v3, s[2:3]
	v_readlane_b32 s2, v242, 34
	v_readlane_b32 s3, v242, 35
	v_mov_b32_e32 v3, v1
	s_mov_b32 m0, s18
	s_add_i32 s21, s18, 0x6000
	s_nop 1
	global_load_lds_dwordx4 v3, s[2:3]
	v_mov_b32_e32 v3, v164
	s_mov_b32 m0, s19
	s_cmp_lg_u32 s0, 1
	global_load_lds_dwordx4 v3, s[2:3]
	v_readlane_b32 s2, v242, 32
	v_readlane_b32 s3, v242, 33
	v_mov_b32_e32 v3, v1
	s_mov_b32 m0, s20
	s_nop 2
	global_load_lds_dwordx4 v3, s[2:3]
	v_mov_b32_e32 v3, v164
	s_mov_b32 m0, s21
	s_nop 0
	global_load_lds_dwordx4 v3, s[2:3]
	s_cbranch_scc1 .LBB0_546
	s_setprio 1
	s_barrier

; #define PG8_WAIT_V(n) asm volatile("s_waitcnt vmcnt(" #n ")" ::: "memory")
; #define PG8_BAR __builtin_amdgcn_s_barrier()
; template <class Epi, class Sched, bool ALIGN_EPI = false, bool SP2 = false>
; __device__ __forceinline__ void gemm_phase(PG8_LAS unsigned char* lds, const Gemm g, const Sched& S, const Epi& E) {
;     ...
;     PG8_WAIT_V(0);
;     if constexpr (!ALIGN_EPI) { if (wr == 0) PG8_BAR; }
;     PG8_BAR;
.LBB0_572:
	s_setprio 0
	s_waitcnt vmcnt(0)
	s_cmpk_gt_u32 s14, 0xff
	s_movk_i32 s48, 0x2000
	s_movk_i32 s49, 0x3000
	s_movk_i32 s46, 0x1ff
	v_readlane_b32 s50, v241, 17
	v_readlane_b32 s40, v241, 42
	s_cbranch_scc1 .LBB0_574
	s_barrier

; #define PG8_STAGE(bufoff, gbase, voff) do { const char* gb_ = (const char*)(gbase); asm volatile("" : "+s"(gb_)); _Pragma("unroll") for (int _i = 0; _i < 2; ++_i) { unsigned vo_ = (voff)[_i]; asm volatile("" : "+v"(vo_));        \
;         __builtin_amdgcn_global_load_lds((const unsigned*)(gb_ + vo_), (PG8_LAS unsigned*)(lds + (bufoff) + ldsw + _i * 8192), 16, 0, 0); } } while (0)
; #define PG8_BAR __builtin_amdgcn_s_barrier()
; template <class Epi, class Sched, bool ALIGN_EPI = false, bool SP2 = false>
; __device__ __forceinline__ void gemm_phase(PG8_LAS unsigned char* lds, const Gemm g, const Sched& S, const Epi& E) {
;     int tid_ = threadIdx.x; asm volatile("" : "+v"(tid_));
;     const int tid = tid_, wid = __builtin_amdgcn_readfirstlane(tid >> 6), lane = tid & 63, wr = wid >> 2, wc = wid & 3, fr = lane & 15, fq = lane >> 4;
;     const int K = g.K, nt = K / BK;
;     unsigned voffA[2], voffB[2];
; #pragma unroll
;     for (int i = 0; i < 2; ++i) { int R, C; stage_rc(tid * 16 + i * 8192, R, C); const int Rb = Epi::PERM ? ((R & ~31) + perm32(R & 31)) : R;
;         voffA[i] = (unsigned)(R * K + C) * 2u; voffB[i] = (unsigned)(Rb * K + C) * 2u; }
;     ...
;     const char* cA = (const char*)g.A + (size_t)cur.pm * tstep; const char* cB = (const char*)g.Bt + (size_t)cur.pn * tstep;
;     S.a_ready(cur);
;     if constexpr (SP2) {
;         PG8_STAGE(PG8_SB(0, 0), cB, voffB); PG8_STAGE(PG8_SB(0, 1), cB + hstep, voffB); PG8_STAGE(PG8_SA(0, 0), cA, voffA); PG8_STAGE(PG8_SA(0, 1), cA + hstep, voffA);
;         if (wr == 1) PG8_BAR;
.LBB0_624:
	s_andn2_b64 vcc, exec, s[0:1]
	s_cbranch_vccnz .LBB0_687
	v_readlane_b32 s0, v242, 3
	s_waitcnt vmcnt(0)
	v_mov_b32_e32 v2, v0
	v_readlane_b32 s1, v242, 4
	s_andn2_b64 vcc, exec, s[0:1]
	v_readfirstlane_b32 s2, v2
	s_cbranch_vccnz .LBB0_641
	v_bfe_i32 v4, v2, 27, 1
	s_waitcnt lgkmcnt(0)
	v_lshlrev_b32_e32 v3, 4, v2
	v_lshrrev_b32_e32 v4, 22, v4
	v_add_u32_e32 v4, v3, v4
	v_and_b32_e32 v4, 0xfffffc00, v4
	v_sub_u32_e32 v4, v3, v4
	v_ashrrev_i32_e32 v1, 31, v2
	v_lshrrev_b32_e32 v5, 4, v4
	v_lshrrev_b32_e32 v1, 26, v1
	v_bitop3_b32 v4, v5, v4, 32 bitop3:0x6c
	v_add_u32_e32 v1, v2, v1
	v_ashrrev_i32_e32 v6, 31, v4
	v_ashrrev_i32_e32 v1, 6, v1
	v_lshrrev_b32_e32 v6, 26, v6
	v_lshlrev_b32_e32 v5, 3, v1
	v_add_u32_e32 v6, v4, v6
	v_readlane_b32 s0, v241, 44
	v_and_b32_e32 v5, -16, v5
	v_ashrrev_i32_e32 v7, 6, v6
	v_and_b32_e32 v6, 0xc0, v6
	s_add_u32 s24, s0, 0x2400000
	v_readlane_b32 s0, v241, 45
	v_add_u32_e32 v5, v7, v5
	v_sub_u32_e32 v4, v4, v6
	s_addc_u32 s25, s0, 0
	v_lshlrev_b32_e32 v1, 5, v1
	v_ashrrev_i16_sdwa v4, v217, sext(v4) dst_sel:DWORD dst_unused:UNUSED_PAD src0_sel:DWORD src1_sel:BYTE_0
	v_lshlrev_b32_e32 v6, 1, v5
	v_lshrrev_b32_e32 v8, 2, v5
	v_and_b32_e32 v7, 3, v7
	s_mov_b32 s0, 0xfffe0
	v_and_b32_e32 v1, 32, v1
	v_bfe_i32 v4, v4, 0, 16
	v_and_b32_e32 v6, 24, v6
	v_and_b32_e32 v8, 4, v8
	v_and_or_b32 v7, v5, s0, v7
	v_or3_b32 v6, v7, v8, v6
	v_add_lshl_u32 v4, v1, v4, 1
	v_add_u32_e32 v3, 0x2000, v3
	v_lshl_add_u32 v1, v5, 12, v4
	v_lshl_add_u32 v162, v6, 12, v4
	v_ashrrev_i32_e32 v4, 31, v3
	v_lshrrev_b32_e32 v4, 22, v4
	v_add_u32_e32 v4, v3, v4
	v_ashrrev_i32_e32 v4, 10, v4
	v_mul_i32_i24_e32 v5, 0x400, v4
	v_sub_u32_e32 v3, v3, v5
	v_lshrrev_b32_e32 v5, 4, v3
	v_bitop3_b32 v3, v5, v3, 32 bitop3:0x6c
	v_ashrrev_i32_e32 v6, 31, v3
	v_lshrrev_b32_e32 v6, 26, v6
	v_lshlrev_b32_e32 v5, 3, v4
	v_add_u32_e32 v6, v3, v6
	v_and_b32_e32 v5, -16, v5
	v_ashrrev_i32_e32 v7, 6, v6
	v_and_b32_e32 v6, 0xc0, v6
	v_add_u32_e32 v5, v7, v5
	v_sub_u32_e32 v3, v3, v6
	v_and_b32_e32 v7, 3, v7
	s_ashr_i32 s4, s2, 6
	s_ashr_i32 s3, s2, 8
	v_lshlrev_b32_e32 v4, 5, v4
	v_ashrrev_i16_sdwa v3, v217, sext(v3) dst_sel:DWORD dst_unused:UNUSED_PAD src0_sel:DWORD src1_sel:BYTE_0
	v_lshlrev_b32_e32 v6, 1, v5
	v_lshrrev_b32_e32 v8, 2, v5
	v_and_or_b32 v7, v5, s0, v7
	s_lshl_b32 s26, s4, 10
	v_readlane_b32 s0, v242, 7
	v_and_b32_e32 v4, 32, v4
	v_bfe_i32 v3, v3, 0, 16
	v_and_b32_e32 v6, 24, v6
	v_and_b32_e32 v8, 4, v8
	v_readlane_b32 s1, v242, 8
	s_add_u32 s16, s24, s0
	v_or3_b32 v6, v7, v8, v6
	v_add_lshl_u32 v3, v4, v3, 1
	s_addc_u32 s17, s25, s1
	v_lshl_add_u32 v164, v5, 12, v3
	v_lshl_add_u32 v184, v6, 12, v3
	s_mov_b64 s[0:1], s[16:17]
	s_add_i32 s27, s26, 0
	v_mov_b32_e32 v3, v162
	s_add_i32 m0, s27, 0x10000
	s_nop 0
	global_load_lds_dwordx4 v3, s[0:1]
	v_mov_b32_e32 v3, v184
	s_add_i32 m0, s27, 0x12000
	s_nop 0
	global_load_lds_dwordx4 v3, s[0:1]
	s_add_u32 s0, s16, 0x80000
	s_addc_u32 s1, s17, 0
	v_mov_b32_e32 v3, v162
	s_add_i32 m0, s27, 0x14000
	s_add_i32 s28, s27, 0x2000
	global_load_lds_dwordx4 v3, s[0:1]
	v_mov_b32_e32 v3, v184
	s_add_i32 m0, s27, 0x16000
	s_add_i32 s29, s27, 0x4000
	global_load_lds_dwordx4 v3, s[0:1]
	v_readlane_b32 s0, v242, 14
	v_readlane_b32 s1, v242, 15
	v_mov_b32_e32 v3, v1
	s_mov_b32 m0, s27
	s_add_i32 s33, s27, 0x6000
	s_nop 1
	global_load_lds_dwordx4 v3, s[0:1]
	v_mov_b32_e32 v3, v164
	s_mov_b32 m0, s28
	s_cmp_eq_u32 s3, 1
	global_load_lds_dwordx4 v3, s[0:1]
	v_readlane_b32 s0, v242, 12
	v_readlane_b32 s1, v242, 13
	v_mov_b32_e32 v3, v1
	s_mov_b32 m0, s29
	s_nop 2
	global_load_lds_dwordx4 v3, s[0:1]
	v_mov_b32_e32 v3, v164
	s_mov_b32 m0, s33
	s_nop 0
	global_load_lds_dwordx4 v3, s[0:1]
	s_cselect_b64 s[0:1], -1, 0
	s_cmp_lg_u32 s3, 1
	s_cbranch_scc1 .LBB0_628
	s_setprio 1
	s_barrier

; #define PG8_WAIT_V(n) asm volatile("s_waitcnt vmcnt(" #n ")" ::: "memory")
; #define PG8_BAR __builtin_amdgcn_s_barrier()
; template <class Epi, class Sched, bool ALIGN_EPI = false, bool SP2 = false>
; __device__ __forceinline__ void gemm_phase(PG8_LAS unsigned char* lds, const Gemm g, const Sched& S, const Epi& E) {
;     ...
;     PG8_WAIT_V(0);
;     if constexpr (!ALIGN_EPI) { if (wr == 0) PG8_BAR; }
;     PG8_BAR;
.LBB0_640:
	s_setprio 0
	s_waitcnt vmcnt(0)
	v_readlane_b32 s4, v243, 2
	v_readlane_b32 s5, v243, 3
	s_movk_i32 s48, 0x2000
	s_movk_i32 s46, 0x1ff
	s_barrier
	v_readlane_b32 s6, v243, 4
	v_readlane_b32 s7, v243, 5
	v_readlane_b32 s8, v243, 6
	v_readlane_b32 s9, v243, 7
	v_readlane_b32 s10, v243, 8
	v_readlane_b32 s11, v243, 9
	v_readlane_b32 s12, v243, 10
	v_readlane_b32 s13, v243, 11
	v_readlane_b32 s14, v243, 12
	v_readlane_b32 s15, v243, 13
	v_readlane_b32 s16, v243, 14
	v_readlane_b32 s17, v243, 15
	v_readlane_b32 s18, v243, 16
	v_readlane_b32 s19, v243, 17
	v_readlane_b32 s40, v241, 42

; #define PG8_STAGE(bufoff, gbase, voff) do { const char* gb_ = (const char*)(gbase); asm volatile("" : "+s"(gb_)); _Pragma("unroll") for (int _i = 0; _i < 2; ++_i) { unsigned vo_ = (voff)[_i]; asm volatile("" : "+v"(vo_));        \
;         __builtin_amdgcn_global_load_lds((const unsigned*)(gb_ + vo_), (PG8_LAS unsigned*)(lds + (bufoff) + ldsw + _i * 8192), 16, 0, 0); } } while (0)
; #define PG8_BAR __builtin_amdgcn_s_barrier()
; template <class Epi, class Sched, bool ALIGN_EPI = false, bool SP2 = false>
; __device__ __forceinline__ void gemm_phase(PG8_LAS unsigned char* lds, const Gemm g, const Sched& S, const Epi& E) {
;     int tid_ = threadIdx.x; asm volatile("" : "+v"(tid_));
;     const int tid = tid_, wid = __builtin_amdgcn_readfirstlane(tid >> 6), lane = tid & 63, wr = wid >> 2, wc = wid & 3, fr = lane & 15, fq = lane >> 4;
;     const int K = g.K, nt = K / BK;
;     unsigned voffA[2], voffB[2];
; #pragma unroll
;     for (int i = 0; i < 2; ++i) { int R, C; stage_rc(tid * 16 + i * 8192, R, C); const int Rb = Epi::PERM ? ((R & ~31) + perm32(R & 31)) : R;
;         voffA[i] = (unsigned)(R * K + C) * 2u; voffB[i] = (unsigned)(Rb * K + C) * 2u; }
;     ...
;     const char* cA = (const char*)g.A + (size_t)cur.pm * tstep; const char* cB = (const char*)g.Bt + (size_t)cur.pn * tstep;
;     S.a_ready(cur);
;     if constexpr (SP2) {
;         PG8_STAGE(PG8_SB(0, 0), cB, voffB); PG8_STAGE(PG8_SB(0, 1), cB + hstep, voffB); PG8_STAGE(PG8_SA(0, 0), cA, voffA); PG8_STAGE(PG8_SA(0, 1), cA + hstep, voffA);
;         if (wr == 1) PG8_BAR;
.LBB0_689:
	s_andn2_b64 vcc, exec, s[0:1]
	s_cbranch_vccnz .LBB0_219
	s_waitcnt vmcnt(0)
	v_mov_b32_e32 v2, v0
	s_add_i32 s33, s8, 1
	s_and_b64 vcc, exec, s[36:37]
	v_readfirstlane_b32 s12, v2
	s_cbranch_vccnz .LBB0_763
	v_bfe_i32 v4, v2, 27, 1
	s_waitcnt lgkmcnt(0)
	v_lshlrev_b32_e32 v3, 4, v2
	v_lshrrev_b32_e32 v4, 22, v4
	v_add_u32_e32 v4, v3, v4
	v_and_b32_e32 v4, 0xfffffc00, v4
	v_sub_u32_e32 v4, v3, v4
	v_lshrrev_b32_e32 v5, 4, v4
	v_ashrrev_i32_e32 v1, 31, v2
	v_bitop3_b32 v4, v5, v4, 32 bitop3:0x6c
	v_lshrrev_b32_e32 v1, 26, v1
	v_ashrrev_i32_e32 v6, 31, v4
	v_add_u32_e32 v1, v2, v1
	v_lshrrev_b32_e32 v6, 26, v6
	v_ashrrev_i32_e32 v1, 6, v1
	v_add_u32_e32 v6, v4, v6
	v_lshlrev_b32_e32 v5, 3, v1
	v_ashrrev_i32_e32 v7, 6, v6
	v_and_b32_e32 v6, 0xc0, v6
	v_and_b32_e32 v5, -16, v5
	v_lshlrev_b32_e32 v1, 5, v1
	v_sub_u32_e32 v4, v4, v6
	v_add_u32_e32 v5, v7, v5
	v_and_b32_e32 v1, 32, v1
	v_ashrrev_i16_sdwa v4, v217, sext(v4) dst_sel:DWORD dst_unused:UNUSED_PAD src0_sel:DWORD src1_sel:BYTE_0
	v_add_u32_sdwa v4, v1, sext(v4) dst_sel:DWORD dst_unused:UNUSED_PAD src0_sel:DWORD src1_sel:WORD_0
	v_lshlrev_b32_e32 v1, 1, v5
	v_lshrrev_b32_e32 v6, 2, v5
	v_and_b32_e32 v7, 3, v7
	s_mov_b32 s1, 0x7fffe0
	v_and_b32_e32 v1, 24, v1
	v_and_b32_e32 v6, 4, v6
	v_and_or_b32 v7, v5, s1, v7
	v_or3_b32 v6, v7, v6, v1
	s_movk_i32 s2, 0x1600
	v_mul_lo_u32 v1, v5, s2
	v_mul_u32_u24_e32 v5, 0x1600, v6
	v_add_u32_e32 v3, 0x2000, v3
	v_add_lshl_u32 v1, v4, v1, 1
	v_add_lshl_u32 v162, v5, v4, 1
	v_ashrrev_i32_e32 v4, 31, v3
	v_lshrrev_b32_e32 v4, 22, v4
	v_add_u32_e32 v4, v3, v4
	v_ashrrev_i32_e32 v4, 10, v4
	v_mul_i32_i24_e32 v5, 0x400, v4
	v_sub_u32_e32 v3, v3, v5
	v_lshrrev_b32_e32 v5, 4, v3
	v_bitop3_b32 v3, v5, v3, 32 bitop3:0x6c
	v_ashrrev_i32_e32 v6, 31, v3
	v_lshrrev_b32_e32 v6, 26, v6
	v_add_u32_e32 v6, v3, v6
	v_lshlrev_b32_e32 v5, 3, v4
	v_ashrrev_i32_e32 v7, 6, v6
	v_and_b32_e32 v6, 0xc0, v6
	v_readlane_b32 s0, v241, 44
	v_and_b32_e32 v5, -16, v5
	v_lshlrev_b32_e32 v4, 5, v4
	v_sub_u32_e32 v3, v3, v6
	s_add_u32 s13, s0, 0x5000000
	v_readlane_b32 s0, v241, 45
	v_add_u32_e32 v5, v7, v5
	v_and_b32_e32 v4, 32, v4
	v_ashrrev_i16_sdwa v3, v217, sext(v3) dst_sel:DWORD dst_unused:UNUSED_PAD src0_sel:DWORD src1_sel:BYTE_0
	v_and_b32_e32 v7, 3, v7
	s_addc_u32 s14, s0, 0
	v_add_u32_sdwa v3, v4, sext(v3) dst_sel:DWORD dst_unused:UNUSED_PAD src0_sel:DWORD src1_sel:WORD_0
	v_lshlrev_b32_e32 v4, 1, v5
	v_lshrrev_b32_e32 v6, 2, v5
	v_and_or_b32 v7, v5, s1, v7
	s_ashr_i32 s1, s12, 6
	v_readlane_b32 s3, v242, 9
	s_ashr_i32 s0, s12, 8
	v_and_b32_e32 v4, 24, v4
	v_and_b32_e32 v6, 4, v6
	v_mul_lo_u32 v5, v5, s2
	s_lshl_b32 s15, s1, 10
	s_mul_i32 s2, s3, 0x2c0000
	v_or3_b32 v4, v7, v6, v4
	s_add_u32 s6, s13, s2
	s_mul_hi_i32 s2, s3, 0x2c0000
	v_mul_u32_u24_e32 v4, 0x1600, v4
	s_addc_u32 s7, s14, s2
	v_add_lshl_u32 v164, v3, v5, 1
	v_add_lshl_u32 v190, v4, v3, 1
	s_mov_b64 s[2:3], s[6:7]
	s_add_i32 s16, s15, 0
	v_mov_b32_e32 v3, v162
	s_add_i32 m0, s16, 0x10000
	s_nop 0
	global_load_lds_dwordx4 v3, s[2:3]
	v_mov_b32_e32 v3, v190
	s_add_i32 m0, s16, 0x12000
	s_nop 0
	global_load_lds_dwordx4 v3, s[2:3]
	s_add_u32 s2, s6, 0x160000
	s_addc_u32 s3, s7, 0
	v_mov_b32_e32 v3, v162
	s_add_i32 m0, s16, 0x14000
	s_add_i32 s17, s16, 0x2000
	global_load_lds_dwordx4 v3, s[2:3]
	v_mov_b32_e32 v3, v190
	s_add_i32 m0, s16, 0x16000
	s_add_i32 s18, s16, 0x4000
	global_load_lds_dwordx4 v3, s[2:3]
	v_readlane_b32 s2, v242, 44
	v_readlane_b32 s3, v242, 45
	v_mov_b32_e32 v3, v1
	s_mov_b32 m0, s16
	s_add_i32 s19, s16, 0x6000
	s_nop 1
	global_load_lds_dwordx4 v3, s[2:3]
	v_mov_b32_e32 v3, v164
	s_mov_b32 m0, s17
	s_cmp_lg_u32 s0, 1
	global_load_lds_dwordx4 v3, s[2:3]
	v_readlane_b32 s2, v242, 42
	v_readlane_b32 s3, v242, 43
	v_mov_b32_e32 v3, v1
	s_mov_b32 m0, s18
	s_nop 2
	global_load_lds_dwordx4 v3, s[2:3]
	v_mov_b32_e32 v3, v164
	s_mov_b32 m0, s19
	s_nop 0
	global_load_lds_dwordx4 v3, s[2:3]
	s_cbranch_scc1 .LBB0_693
	s_setprio 1
	s_barrier

; #define PG8_WAIT_V(n) asm volatile("s_waitcnt vmcnt(" #n ")" ::: "memory")
; #define PG8_BAR __builtin_amdgcn_s_barrier()
; template <class Epi, class Sched, bool ALIGN_EPI = false, bool SP2 = false>
; __device__ __forceinline__ void gemm_phase(PG8_LAS unsigned char* lds, const Gemm g, const Sched& S, const Epi& E) {
;     ...
;     PG8_WAIT_V(0);
;     if constexpr (!ALIGN_EPI) { if (wr == 0) PG8_BAR; }
;     PG8_BAR;
.LBB0_760:
	s_setprio 0
	s_waitcnt vmcnt(0)
	s_cmpk_gt_u32 s12, 0xff
	s_movk_i32 s48, 0x2000
	s_movk_i32 s49, 0x3000
	s_movk_i32 s46, 0x1ff
	v_readlane_b32 s50, v241, 17
	s_mov_b32 s51, 0xd800000
	v_readlane_b32 s40, v241, 42
	s_cbranch_scc1 .LBB0_762
	s_barrier
